# combo
# baseline (speedup 1.0000x reference)
; template <int EPI>
; __device__ __forceinline__ void gemm_phase(const GemmArgs& G, char* shm) {
;   const int nwg = G.nM * G.nN;
;   const int vb = vbid();
;   for (int t = vb; t < nwg; t += gridDim.x) {
;     int brow, bcol, nbrow = 0, nbcol = 0; gemm_map_tile(G, t, brow, bcol);
;     const bool has_next = t + (int)gridDim.x < nwg;
;     if (has_next) gemm_map_tile(G, t + gridDim.x, nbrow, nbcol);
;     gemm_tile<EPI>(G, brow, bcol, shm, t == vb, has_next, nbrow, nbcol);
;   }
.LBB0_738:
	v_readfirstlane_b32 s6, v224
	s_nop 3
	s_bitcmp0_b32 s6, 8
	s_cbranch_scc0 .Lmy_nobar_1
	s_barrier

; #define STAGE_A(P, br, kt) do { const char* _base = (const char*)(((kt) < G.ksplit ? G.A1 : A2m) + (long)(br) * G.lda + (long)(kt) * BK); \
;     __builtin_amdgcn_global_load_lds((const unsigned*)(_base + aoff0), (unsigned*)((char*)(P) + sb0), 16, 0, 0); \
;     __builtin_amdgcn_global_load_lds((const unsigned*)(_base + aoff1), (unsigned*)((char*)(P) + sb1), 16, 0, 0); } while (0)
; #define LDA(dst, b, h) for (int m = 0; m < 4; ++m) for (int k = 0; k < 2; ++k) \
;     dst[m][k] = *reinterpret_cast<const bf16x8*>(a_rd + ((b) * 2 + (h)) * (HT * 2) + m * 2048 + k * 1024)
; #define LDB(dst, b, h) for (int n = 0; n < 2; ++n) for (int k = 0; k < 2; ++k) \
;     dst[n][k] = *reinterpret_cast<const bf16x8*>(b_rd + ((b) * 2 + (h)) * (HT * 2) + n * 2048 + k * 1024)
; #define MMA(ai, bj, At_, Bt_) do { __builtin_amdgcn_s_setprio(1); \
;     for (int m = 0; m < 4; ++m) for (int n = 0; n < 2; ++n) for (int k = 0; k < 2; ++k) \
;       acc[ai][bj][m][n] = __builtin_amdgcn_mfma_f32_16x16x32_bf16(Bt_[n][k], At_[m][k], acc[ai][bj][m][n], 0, 0, 0); \
;     __builtin_amdgcn_s_setprio(0); } while (0)
; #define WAIT_V(n) asm volatile("s_waitcnt vmcnt(" #n ")" ::: "memory")
; #define WAIT_L(n) asm volatile("s_waitcnt lgkmcnt(" #n ")" ::: "memory")
; #define BAR __builtin_amdgcn_s_barrier()
;     ...
;   float ssv[2][4] = {};
;   if constexpr (EPI == EPI_GU || EPI == EPI_EVIN || EPI == EPI_ODIN) {
; #pragma unroll
;     for (int ai = 0; ai < 2; ++ai)
; #pragma unroll
;       for (int m = 0; m < 4; ++m) ssv[ai][m] = G.ssr[brow + ai * HALF + wr * 64 + m * 16 + fr];
;   }
;   { LDB(B0, 0, 0); LDA(At, 0, 0); STAGE_A(SA(1, 1), brow + HALF, nt - 1);
;     BAR; WAIT_L(0); MMA(0, 0, At, B0); BAR;
;     LDB(B1, 0, 1); BAR; WAIT_L(0); MMA(0, 1, At, B1); BAR;
;     LDA(At, 0, 1); WAIT_V(4); BAR; WAIT_L(0); MMA(1, 0, At, B0); MMA(1, 1, At, B1); BAR; }
.Lmy_kexit_0:
	s_waitcnt vmcnt(6)
	v_not_b32_e32 v250, 63
	v_mov_b32_e32 v251, 0x41b17218
	v_or_b32_e32 v130, s40, v150
	v_lshl_add_u32 v130, v148, 6, v130
	v_ashrrev_i32_e32 v131, 31, v130
	v_lshl_add_u64 v[132:133], v[130:131], 2, s[30:31]
	v_add_u32_e32 v134, 0x80, v130
	v_add_u32_e32 v136, 0x90, v130
	v_add_u32_e32 v138, 0xa0, v130
	v_add_u32_e32 v130, 0xb0, v130
	s_or_b32 s57, s40, 0x80
	v_ashrrev_i32_e32 v135, 31, v134
	v_ashrrev_i32_e32 v137, 31, v136
	v_ashrrev_i32_e32 v139, 31, v138
	v_ashrrev_i32_e32 v131, 31, v130
	s_mul_i32 s8, s57, 0x1080
	v_lshl_add_u64 v[134:135], v[134:135], 2, s[30:31]
	v_lshl_add_u64 v[136:137], v[136:137], 2, s[30:31]
	v_lshl_add_u64 v[138:139], v[138:139], 2, s[30:31]
	v_lshl_add_u64 v[140:141], v[130:131], 2, s[30:31]
	global_load_dword v130, v[132:133], off
	global_load_dword v146, v[132:133], off offset:64
	global_load_dword v148, v[132:133], off offset:128
	global_load_dword v156, v[132:133], off offset:192
	global_load_dword v154, v[134:135], off
	global_load_dword v153, v[136:137], off
	global_load_dword v152, v[138:139], off
	global_load_dword v150, v[140:141], off
	s_mul_hi_i32 s9, s57, 0x1080
	s_add_u32 s8, s12, s8
	s_addc_u32 s9, s13, s9
	v_lshl_add_u64 v[140:141], s[8:9], 0, v[180:181]
	s_mov_b64 s[22:23], 0xf80
	v_readfirstlane_b32 s10, v162
	v_lshl_add_u64 v[140:141], v[140:141], 0, s[22:23]
	s_mov_b32 m0, s10
	ds_read_b128 v[132:135], v155
	ds_read_b128 v[136:139], v155 offset:1024
	ds_read_b128 v[164:167], v155 offset:2048
	ds_read_b128 v[168:171], v155 offset:3072
	ds_read_b128 v[172:175], v151
	ds_read_b128 v[176:179], v151 offset:1024
	ds_read_b128 v[182:185], v151 offset:2048
	ds_read_b128 v[186:189], v151 offset:3072
	ds_read_b128 v[190:193], v151 offset:4096
	ds_read_b128 v[194:197], v151 offset:5120
	ds_read_b128 v[198:201], v151 offset:6144
	ds_read_b128 v[202:205], v151 offset:7168
	global_load_lds_dwordx4 v[140:141], off
	v_lshl_add_u64 v[140:141], s[8:9], 0, v[128:129]
	v_readfirstlane_b32 s8, v163
	v_lshl_add_u64 v[140:141], v[140:141], 0, s[22:23]
	s_mov_b32 m0, s8
	s_nop 0
	global_load_lds_dwordx4 v[140:141], off
	s_barrier
	s_waitcnt lgkmcnt(0)
	s_setprio 1
	s_waitcnt lgkmcnt(0)
	v_mfma_f32_16x16x32_bf16 v[124:127], v[132:135], v[172:175], v[124:127]
	v_mfma_f32_16x16x32_bf16 v[120:123], v[164:167], v[172:175], v[120:123]
	v_mfma_f32_16x16x32_bf16 v[116:119], v[132:135], v[182:185], v[116:119]
	v_mfma_f32_16x16x32_bf16 v[112:115], v[164:167], v[182:185], v[112:115]
	v_mfma_f32_16x16x32_bf16 v[108:111], v[132:135], v[190:193], v[108:111]
	v_mfma_f32_16x16x32_bf16 v[104:107], v[164:167], v[190:193], v[104:107]
	v_mfma_f32_16x16x32_bf16 v[100:103], v[132:135], v[198:201], v[100:103]
	v_mfma_f32_16x16x32_bf16 v[96:99], v[164:167], v[198:201], v[96:99]
	v_mfma_f32_16x16x32_bf16 v[124:127], v[136:139], v[176:179], v[124:127]
	v_mfma_f32_16x16x32_bf16 v[120:123], v[168:171], v[176:179], v[120:123]
	v_mfma_f32_16x16x32_bf16 v[116:119], v[136:139], v[186:189], v[116:119]
	v_mfma_f32_16x16x32_bf16 v[112:115], v[168:171], v[186:189], v[112:115]
	v_mfma_f32_16x16x32_bf16 v[108:111], v[136:139], v[194:197], v[108:111]
	v_mfma_f32_16x16x32_bf16 v[104:107], v[168:171], v[194:197], v[104:107]
	s_setprio 2
	s_barrier
	v_mfma_f32_16x16x32_bf16 v[100:103], v[136:139], v[202:205], v[100:103]
	v_mfma_f32_16x16x32_bf16 v[96:99], v[168:171], v[202:205], v[96:99]
	s_setprio 0
	ds_read_b128 v[206:209], v155 offset:16384
	ds_read_b128 v[210:213], v155 offset:17408
	ds_read_b128 v[214:217], v155 offset:18432
	ds_read_b128 v[218:221], v155 offset:19456
	s_barrier
	s_waitcnt lgkmcnt(0)
	s_setprio 1
	s_waitcnt lgkmcnt(0)
	v_mfma_f32_16x16x32_bf16 v[92:95], v[206:209], v[172:175], v[92:95]
	v_mfma_f32_16x16x32_bf16 v[88:91], v[214:217], v[172:175], v[88:91]
	v_mfma_f32_16x16x32_bf16 v[84:87], v[206:209], v[182:185], v[84:87]
	v_mfma_f32_16x16x32_bf16 v[80:83], v[214:217], v[182:185], v[80:83]
	v_mfma_f32_16x16x32_bf16 v[76:79], v[206:209], v[190:193], v[76:79]
	v_mfma_f32_16x16x32_bf16 v[72:75], v[214:217], v[190:193], v[72:75]
	v_mfma_f32_16x16x32_bf16 v[68:71], v[206:209], v[198:201], v[68:71]
	v_mfma_f32_16x16x32_bf16 v[64:67], v[214:217], v[198:201], v[64:67]
	v_mfma_f32_16x16x32_bf16 v[92:95], v[210:213], v[176:179], v[92:95]
	v_mfma_f32_16x16x32_bf16 v[88:91], v[218:221], v[176:179], v[88:91]
	v_mfma_f32_16x16x32_bf16 v[84:87], v[210:213], v[186:189], v[84:87]
	v_mfma_f32_16x16x32_bf16 v[80:83], v[218:221], v[186:189], v[80:83]
	v_mfma_f32_16x16x32_bf16 v[76:79], v[210:213], v[194:197], v[76:79]
	v_mfma_f32_16x16x32_bf16 v[72:75], v[218:221], v[194:197], v[72:75]
	s_setprio 2
	s_barrier
	v_mfma_f32_16x16x32_bf16 v[68:71], v[210:213], v[202:205], v[68:71]
	v_mfma_f32_16x16x32_bf16 v[64:67], v[218:221], v[202:205], v[64:67]
	s_setprio 0
	ds_read_b128 v[172:175], v151 offset:16384
	ds_read_b128 v[176:179], v151 offset:17408
	ds_read_b128 v[182:185], v151 offset:18432
	ds_read_b128 v[186:189], v151 offset:19456
	ds_read_b128 v[190:193], v151 offset:20480
	ds_read_b128 v[194:197], v151 offset:21504
	ds_read_b128 v[198:201], v151 offset:22528
	ds_read_b128 v[202:205], v151 offset:23552
	s_waitcnt vmcnt(4)
	s_barrier
; #define STAGE_A(P, br, kt) do { const char* _base = (const char*)(((kt) < G.ksplit ? G.A1 : A2m) + (long)(br) * G.lda + (long)(kt) * BK); \
;     __builtin_amdgcn_global_load_lds((const unsigned*)(_base + aoff0), (unsigned*)((char*)(P) + sb0), 16, 0, 0); \
;     __builtin_amdgcn_global_load_lds((const unsigned*)(_base + aoff1), (unsigned*)((char*)(P) + sb1), 16, 0, 0); } while (0)
; #define LDA(dst, b, h) for (int m = 0; m < 4; ++m) for (int k = 0; k < 2; ++k) \
;     dst[m][k] = *reinterpret_cast<const bf16x8*>(a_rd + ((b) * 2 + (h)) * (HT * 2) + m * 2048 + k * 1024)
; #define LDB(dst, b, h) for (int n = 0; n < 2; ++n) for (int k = 0; k < 2; ++k) \
;     dst[n][k] = *reinterpret_cast<const bf16x8*>(b_rd + ((b) * 2 + (h)) * (HT * 2) + n * 2048 + k * 1024)
; #define MMA(ai, bj, At_, Bt_) do { __builtin_amdgcn_s_setprio(1); \
;     for (int m = 0; m < 4; ++m) for (int n = 0; n < 2; ++n) for (int k = 0; k < 2; ++k) \
;       acc[ai][bj][m][n] = __builtin_amdgcn_mfma_f32_16x16x32_bf16(Bt_[n][k], At_[m][k], acc[ai][bj][m][n], 0, 0, 0); \
;     __builtin_amdgcn_s_setprio(0); } while (0)
; #define WAIT_V(n) asm volatile("s_waitcnt vmcnt(" #n ")" ::: "memory")
; #define WAIT_L(n) asm volatile("s_waitcnt lgkmcnt(" #n ")" ::: "memory")
; #define BAR __builtin_amdgcn_s_barrier()
;     ...
;   { LDB(B0, 0, 0); LDA(At, 0, 0); STAGE_A(SA(1, 1), brow + HALF, nt - 1);
;     BAR; WAIT_L(0); MMA(0, 0, At, B0); BAR;
;     LDB(B1, 0, 1); BAR; WAIT_L(0); MMA(0, 1, At, B1); BAR;
;     LDA(At, 0, 1); WAIT_V(4); BAR; WAIT_L(0); MMA(1, 0, At, B0); MMA(1, 1, At, B1); BAR; }
;   { LDB(B0, 1, 0); LDA(At, 1, 0); WAIT_V(2); BAR; WAIT_L(0); MMA(0, 0, At, B0); BAR;
;     LDB(B1, 1, 1); WAIT_V(0); BAR; WAIT_L(0); MMA(0, 1, At, B1); BAR;
;     LDA(At, 1, 1); BAR; WAIT_L(0); MMA(1, 0, At, B0); MMA(1, 1, At, B1); BAR; }
	s_waitcnt lgkmcnt(0)
	s_setprio 1
	s_waitcnt lgkmcnt(0)
	v_mfma_f32_16x16x32_bf16 v[60:63], v[132:135], v[172:175], v[60:63]
	v_mfma_f32_16x16x32_bf16 v[56:59], v[164:167], v[172:175], v[56:59]
	v_mfma_f32_16x16x32_bf16 v[52:55], v[132:135], v[182:185], v[52:55]
	v_mfma_f32_16x16x32_bf16 v[48:51], v[164:167], v[182:185], v[48:51]
	v_mfma_f32_16x16x32_bf16 v[44:47], v[132:135], v[190:193], v[44:47]
	v_mfma_f32_16x16x32_bf16 v[40:43], v[164:167], v[190:193], v[40:43]
	v_mfma_f32_16x16x32_bf16 v[36:39], v[132:135], v[198:201], v[36:39]
	v_mfma_f32_16x16x32_bf16 v[32:35], v[164:167], v[198:201], v[32:35]
	v_mfma_f32_16x16x32_bf16 v[60:63], v[136:139], v[176:179], v[60:63]
	v_mfma_f32_16x16x32_bf16 v[56:59], v[168:171], v[176:179], v[56:59]
	v_mfma_f32_16x16x32_bf16 v[52:55], v[136:139], v[186:189], v[52:55]
	v_mfma_f32_16x16x32_bf16 v[48:51], v[168:171], v[186:189], v[48:51]
	v_mfma_f32_16x16x32_bf16 v[44:47], v[136:139], v[194:197], v[44:47]
	v_mfma_f32_16x16x32_bf16 v[40:43], v[168:171], v[194:197], v[40:43]
	v_mfma_f32_16x16x32_bf16 v[36:39], v[136:139], v[202:205], v[36:39]
	v_mfma_f32_16x16x32_bf16 v[32:35], v[168:171], v[202:205], v[32:35]
	s_setprio 0
	s_setprio 1
	v_mfma_f32_16x16x32_bf16 v[28:31], v[206:209], v[172:175], v[28:31]
	v_mfma_f32_16x16x32_bf16 v[24:27], v[214:217], v[172:175], v[24:27]
	v_mfma_f32_16x16x32_bf16 v[20:23], v[206:209], v[182:185], v[20:23]
	v_mfma_f32_16x16x32_bf16 v[16:19], v[214:217], v[182:185], v[16:19]
	v_mfma_f32_16x16x32_bf16 v[12:15], v[206:209], v[190:193], v[12:15]
	v_mfma_f32_16x16x32_bf16 v[8:11], v[214:217], v[190:193], v[8:11]
	v_mfma_f32_16x16x32_bf16 v[4:7], v[206:209], v[198:201], v[4:7]
	v_mfma_f32_16x16x32_bf16 v[0:3], v[214:217], v[198:201], v[0:3]
	v_mfma_f32_16x16x32_bf16 v[28:31], v[210:213], v[176:179], v[28:31]
	v_mfma_f32_16x16x32_bf16 v[24:27], v[218:221], v[176:179], v[24:27]
	v_mfma_f32_16x16x32_bf16 v[20:23], v[210:213], v[186:189], v[20:23]
	v_mfma_f32_16x16x32_bf16 v[16:19], v[218:221], v[186:189], v[16:19]
	v_mfma_f32_16x16x32_bf16 v[12:15], v[210:213], v[194:197], v[12:15]
	v_mfma_f32_16x16x32_bf16 v[8:11], v[218:221], v[194:197], v[8:11]
	s_setprio 2
	s_barrier
	v_mfma_f32_16x16x32_bf16 v[4:7], v[210:213], v[202:205], v[4:7]
	v_mfma_f32_16x16x32_bf16 v[0:3], v[218:221], v[202:205], v[0:3]
	s_setprio 0
	ds_read_b128 v[132:135], v155 offset:32768
	ds_read_b128 v[136:139], v155 offset:33792
	ds_read_b128 v[162:165], v155 offset:34816
	ds_read_b128 v[166:169], v155 offset:35840
	ds_read_b128 v[170:173], v151 offset:32768
	ds_read_b128 v[174:177], v151 offset:33792
	ds_read_b128 v[182:185], v151 offset:34816
	ds_read_b128 v[186:189], v151 offset:35840
	ds_read_b128 v[190:193], v151 offset:36864
	ds_read_b128 v[194:197], v151 offset:37888
	ds_read_b128 v[198:201], v151 offset:38912
	ds_read_b128 v[202:205], v151 offset:39936
	s_waitcnt vmcnt(2)
	s_barrier
	s_waitcnt lgkmcnt(0)
	s_setprio 1
	s_waitcnt lgkmcnt(0)
	v_mfma_f32_16x16x32_bf16 v[124:127], v[132:135], v[170:173], v[124:127]
	v_mfma_f32_16x16x32_bf16 v[120:123], v[162:165], v[170:173], v[120:123]
	v_mfma_f32_16x16x32_bf16 v[116:119], v[132:135], v[182:185], v[116:119]
	v_mfma_f32_16x16x32_bf16 v[112:115], v[162:165], v[182:185], v[112:115]
	v_mfma_f32_16x16x32_bf16 v[108:111], v[132:135], v[190:193], v[108:111]
	v_mfma_f32_16x16x32_bf16 v[104:107], v[162:165], v[190:193], v[104:107]
	v_mfma_f32_16x16x32_bf16 v[100:103], v[132:135], v[198:201], v[100:103]
	v_mfma_f32_16x16x32_bf16 v[96:99], v[162:165], v[198:201], v[96:99]
	v_mfma_f32_16x16x32_bf16 v[124:127], v[136:139], v[174:177], v[124:127]
	v_mfma_f32_16x16x32_bf16 v[120:123], v[166:169], v[174:177], v[120:123]
	v_mfma_f32_16x16x32_bf16 v[116:119], v[136:139], v[186:189], v[116:119]
	v_mfma_f32_16x16x32_bf16 v[112:115], v[166:169], v[186:189], v[112:115]
	v_mfma_f32_16x16x32_bf16 v[108:111], v[136:139], v[194:197], v[108:111]
	v_mfma_f32_16x16x32_bf16 v[104:107], v[166:169], v[194:197], v[104:107]
	s_setprio 2
	s_barrier
	v_mfma_f32_16x16x32_bf16 v[100:103], v[136:139], v[202:205], v[100:103]
	v_mfma_f32_16x16x32_bf16 v[96:99], v[166:169], v[202:205], v[96:99]
	s_setprio 0
	ds_read_b128 v[206:209], v155 offset:49152
	ds_read_b128 v[210:213], v155 offset:50176
	ds_read_b128 v[214:217], v155 offset:51200
	ds_read_b128 v[218:221], v155 offset:52224
	s_waitcnt vmcnt(0)
	s_barrier
	s_waitcnt lgkmcnt(0)
	s_setprio 1
	s_waitcnt lgkmcnt(0)
	v_mfma_f32_16x16x32_bf16 v[92:95], v[206:209], v[170:173], v[92:95]
	v_mfma_f32_16x16x32_bf16 v[88:91], v[214:217], v[170:173], v[88:91]
	v_mfma_f32_16x16x32_bf16 v[84:87], v[206:209], v[182:185], v[84:87]
	v_mfma_f32_16x16x32_bf16 v[80:83], v[214:217], v[182:185], v[80:83]
	v_mfma_f32_16x16x32_bf16 v[76:79], v[206:209], v[190:193], v[76:79]
	v_mfma_f32_16x16x32_bf16 v[72:75], v[214:217], v[190:193], v[72:75]
	v_mfma_f32_16x16x32_bf16 v[68:71], v[206:209], v[198:201], v[68:71]
	v_mfma_f32_16x16x32_bf16 v[64:67], v[214:217], v[198:201], v[64:67]
	v_mfma_f32_16x16x32_bf16 v[92:95], v[210:213], v[174:177], v[92:95]
	v_mfma_f32_16x16x32_bf16 v[88:91], v[218:221], v[174:177], v[88:91]
	v_mfma_f32_16x16x32_bf16 v[84:87], v[210:213], v[186:189], v[84:87]
	v_mfma_f32_16x16x32_bf16 v[80:83], v[218:221], v[186:189], v[80:83]
	v_mfma_f32_16x16x32_bf16 v[76:79], v[210:213], v[194:197], v[76:79]
	v_mfma_f32_16x16x32_bf16 v[72:75], v[218:221], v[194:197], v[72:75]
	s_setprio 2
	s_barrier
; #define STAGE_A(P, br, kt) do { const char* _base = (const char*)(((kt) < G.ksplit ? G.A1 : A2m) + (long)(br) * G.lda + (long)(kt) * BK); \
;     __builtin_amdgcn_global_load_lds((const unsigned*)(_base + aoff0), (unsigned*)((char*)(P) + sb0), 16, 0, 0); \
;     __builtin_amdgcn_global_load_lds((const unsigned*)(_base + aoff1), (unsigned*)((char*)(P) + sb1), 16, 0, 0); } while (0)
; #define STAGE_B(P, br, kt) do { const char* _base = (const char*)(G.Bt + (long)(br) * G.ldb + (long)(kt) * BK); \
;     __builtin_amdgcn_global_load_lds((const unsigned*)(_base + boff0), (unsigned*)((char*)(P) + sb0), 16, 0, 0); \
;     __builtin_amdgcn_global_load_lds((const unsigned*)(_base + boff1), (unsigned*)((char*)(P) + sb1), 16, 0, 0); } while (0)
; #define LDA(dst, b, h) for (int m = 0; m < 4; ++m) for (int k = 0; k < 2; ++k) \
;     dst[m][k] = *reinterpret_cast<const bf16x8*>(a_rd + ((b) * 2 + (h)) * (HT * 2) + m * 2048 + k * 1024)
; #define LDB(dst, b, h) for (int n = 0; n < 2; ++n) for (int k = 0; k < 2; ++k) \
;     dst[n][k] = *reinterpret_cast<const bf16x8*>(b_rd + ((b) * 2 + (h)) * (HT * 2) + n * 2048 + k * 1024)
; #define MMA(ai, bj, At_, Bt_) do { __builtin_amdgcn_s_setprio(1); \
;     for (int m = 0; m < 4; ++m) for (int n = 0; n < 2; ++n) for (int k = 0; k < 2; ++k) \
;       acc[ai][bj][m][n] = __builtin_amdgcn_mfma_f32_16x16x32_bf16(Bt_[n][k], At_[m][k], acc[ai][bj][m][n], 0, 0, 0); \
;     __builtin_amdgcn_s_setprio(0); } while (0)
; #define WAIT_V(n) asm volatile("s_waitcnt vmcnt(" #n ")" ::: "memory")
; #define WAIT_L(n) asm volatile("s_waitcnt lgkmcnt(" #n ")" ::: "memory")
; #define BAR __builtin_amdgcn_s_barrier()
;     ...
;   { LDB(B0, 1, 0); LDA(At, 1, 0); WAIT_V(2); BAR; WAIT_L(0); MMA(0, 0, At, B0); BAR;
;     LDB(B1, 1, 1); WAIT_V(0); BAR; WAIT_L(0); MMA(0, 1, At, B1); BAR;
;     LDA(At, 1, 1); BAR; WAIT_L(0); MMA(1, 0, At, B0); MMA(1, 1, At, B1); BAR; }
;   if (wr == 0) BAR;
;   if (EPI != EPI_RESID && has_next) {
;     STAGE_B(SB(0, 0), nbcol, 0); STAGE_A(SA(0, 0), nbrow, 0);
;     STAGE_B(SB(0, 1), nbcol + HALF, 0); STAGE_A(SA(0, 1), nbrow + HALF, 0);
;   }
	v_mfma_f32_16x16x32_bf16 v[68:71], v[210:213], v[202:205], v[68:71]
	v_mfma_f32_16x16x32_bf16 v[64:67], v[218:221], v[202:205], v[64:67]
	s_setprio 0
	ds_read_b128 v[170:173], v151 offset:49152
	ds_read_b128 v[174:177], v151 offset:50176
	ds_read_b128 v[182:185], v151 offset:51200
	ds_read_b128 v[186:189], v151 offset:52224
	ds_read_b128 v[190:193], v151 offset:53248
	ds_read_b128 v[194:197], v151 offset:54272
	ds_read_b128 v[198:201], v151 offset:55296
	ds_read_b128 v[202:205], v151 offset:56320
	s_barrier
	s_waitcnt lgkmcnt(0)
	s_setprio 1
	s_waitcnt lgkmcnt(0)
	v_mfma_f32_16x16x32_bf16 v[60:63], v[132:135], v[170:173], v[60:63]
	v_mfma_f32_16x16x32_bf16 v[56:59], v[162:165], v[170:173], v[56:59]
	v_mfma_f32_16x16x32_bf16 v[52:55], v[132:135], v[182:185], v[52:55]
	v_mfma_f32_16x16x32_bf16 v[48:51], v[162:165], v[182:185], v[48:51]
	v_mfma_f32_16x16x32_bf16 v[44:47], v[132:135], v[190:193], v[44:47]
	v_mfma_f32_16x16x32_bf16 v[40:43], v[162:165], v[190:193], v[40:43]
	v_mfma_f32_16x16x32_bf16 v[36:39], v[132:135], v[198:201], v[36:39]
	v_mfma_f32_16x16x32_bf16 v[32:35], v[162:165], v[198:201], v[32:35]
	v_mfma_f32_16x16x32_bf16 v[60:63], v[136:139], v[174:177], v[60:63]
	v_mfma_f32_16x16x32_bf16 v[56:59], v[166:169], v[174:177], v[56:59]
	v_mfma_f32_16x16x32_bf16 v[52:55], v[136:139], v[186:189], v[52:55]
	v_mfma_f32_16x16x32_bf16 v[48:51], v[166:169], v[186:189], v[48:51]
	v_mfma_f32_16x16x32_bf16 v[44:47], v[136:139], v[194:197], v[44:47]
	v_mfma_f32_16x16x32_bf16 v[40:43], v[166:169], v[194:197], v[40:43]
	v_mfma_f32_16x16x32_bf16 v[36:39], v[136:139], v[202:205], v[36:39]
	v_mfma_f32_16x16x32_bf16 v[32:35], v[166:169], v[202:205], v[32:35]
	s_setprio 0
	s_setprio 1
	v_mfma_f32_16x16x32_bf16 v[28:31], v[206:209], v[170:173], v[28:31]
	v_mfma_f32_16x16x32_bf16 v[24:27], v[214:217], v[170:173], v[24:27]
	v_mfma_f32_16x16x32_bf16 v[20:23], v[206:209], v[182:185], v[20:23]
	v_mfma_f32_16x16x32_bf16 v[16:19], v[214:217], v[182:185], v[16:19]
	v_mfma_f32_16x16x32_bf16 v[12:15], v[206:209], v[190:193], v[12:15]
	v_mfma_f32_16x16x32_bf16 v[8:11], v[214:217], v[190:193], v[8:11]
	v_mfma_f32_16x16x32_bf16 v[4:7], v[206:209], v[198:201], v[4:7]
	v_mfma_f32_16x16x32_bf16 v[0:3], v[214:217], v[198:201], v[0:3]
	v_mfma_f32_16x16x32_bf16 v[28:31], v[210:213], v[174:177], v[28:31]
	v_mfma_f32_16x16x32_bf16 v[24:27], v[218:221], v[174:177], v[24:27]
	v_mfma_f32_16x16x32_bf16 v[20:23], v[210:213], v[186:189], v[20:23]
	v_mfma_f32_16x16x32_bf16 v[16:19], v[218:221], v[186:189], v[16:19]
	v_mfma_f32_16x16x32_bf16 v[12:15], v[210:213], v[194:197], v[12:15]
	v_mfma_f32_16x16x32_bf16 v[8:11], v[218:221], v[194:197], v[8:11]
	s_setprio 2
	s_barrier
	v_mfma_f32_16x16x32_bf16 v[4:7], v[210:213], v[202:205], v[4:7]
	v_mfma_f32_16x16x32_bf16 v[0:3], v[218:221], v[202:205], v[0:3]
	s_setprio 0
	s_andn2_b64 vcc, exec, s[6:7]
	s_cbranch_vccnz .LBB0_751
	s_mul_i32 s6, s41, 0x840
	s_ashr_i32 s7, s6, 31
	s_lshl_b64 s[6:7], s[6:7], 1
	s_add_u32 s6, s49, s6
	s_addc_u32 s7, s50, s7
	v_readfirstlane_b32 s8, v159
	v_lshl_add_u64 v[132:133], s[6:7], 0, v[180:181]
	s_mov_b32 m0, s8
	s_mul_i32 s8, s38, 0x1080
	global_load_lds_dwordx4 v[132:133], off
	v_lshl_add_u64 v[132:133], s[6:7], 0, v[128:129]
	v_readfirstlane_b32 s6, v160
	s_mov_b32 m0, s6
	s_mul_hi_i32 s7, s38, 0x1080
	s_add_u32 s6, s12, s8
	s_addc_u32 s7, s13, s7
	v_readfirstlane_b32 s9, v149
	global_load_lds_dwordx4 v[132:133], off
	v_lshl_add_u64 v[132:133], s[6:7], 0, v[180:181]
	s_mov_b32 m0, s9
	v_readfirstlane_b32 s9, v145
	global_load_lds_dwordx4 v[132:133], off
	v_lshl_add_u64 v[132:133], s[6:7], 0, v[128:129]
	v_readfirstlane_b32 s6, v147
	s_mov_b32 m0, s6
	s_or_b32 s6, s41, 0x80
	s_mul_hi_i32 s7, s6, 0x1080
	s_mulk_i32 s6, 0x1080
	s_add_u32 s6, s49, s6
	s_addc_u32 s7, s50, s7
	global_load_lds_dwordx4 v[132:133], off
	v_lshl_add_u64 v[132:133], s[6:7], 0, v[180:181]
	s_mov_b32 m0, s9
	s_add_i32 s8, s8, 0x84000
	global_load_lds_dwordx4 v[132:133], off
	v_lshl_add_u64 v[132:133], s[6:7], 0, v[128:129]
	v_readfirstlane_b32 s6, v161
	s_mov_b32 m0, s6
	s_add_i32 s6, s38, 0x80
	s_mul_hi_i32 s7, s6, 0x1080
	s_add_u32 s6, s12, s8
	s_addc_u32 s7, s13, s7
	v_readfirstlane_b32 s8, v143
	global_load_lds_dwordx4 v[132:133], off
	v_lshl_add_u64 v[132:133], s[6:7], 0, v[180:181]
	s_mov_b32 m0, s8
	v_lshl_add_u64 v[128:129], s[6:7], 0, v[128:129]
	v_readfirstlane_b32 s6, v142
	global_load_lds_dwordx4 v[132:133], off
	s_mov_b32 m0, s6
	s_nop 0
	global_load_lds_dwordx4 v[128:129], off

; template <int EPI>
; __device__ __forceinline__ void gemm_phase(const GemmArgs& G, char* shm) {
;   const int nwg = G.nM * G.nN;
;   const int vb = vbid();
;   for (int t = vb; t < nwg; t += gridDim.x) {
;     int brow, bcol, nbrow = 0, nbcol = 0; gemm_map_tile(G, t, brow, bcol);
;     const bool has_next = t + (int)gridDim.x < nwg;
;     if (has_next) gemm_map_tile(G, t + gridDim.x, nbrow, nbcol);
;     gemm_tile<EPI>(G, brow, bcol, shm, t == vb, has_next, nbrow, nbcol);
;   }
.LBB0_1856:
.Lmy_ev_done:
	v_readfirstlane_b32 s6, v224
	s_nop 3
	s_bitcmp0_b32 s6, 8
	s_cbranch_scc0 .Lmy_nobar_2
	s_barrier
.Lmy_nobar_2:
	s_andn2_b64 vcc, exec, s[22:23]
	s_mov_b32 s24, s41
	s_cbranch_vccz .LBB0_2254

; #define STAGE_A(P, br, kt) do { const char* _base = (const char*)(((kt) < G.ksplit ? G.A1 : A2m) + (long)(br) * G.lda + (long)(kt) * BK); \
;     __builtin_amdgcn_global_load_lds((const unsigned*)(_base + aoff0), (unsigned*)((char*)(P) + sb0), 16, 0, 0); \
;     __builtin_amdgcn_global_load_lds((const unsigned*)(_base + aoff1), (unsigned*)((char*)(P) + sb1), 16, 0, 0); } while (0)
; #define LDA(dst, b, h) for (int m = 0; m < 4; ++m) for (int k = 0; k < 2; ++k) \
;     dst[m][k] = *reinterpret_cast<const bf16x8*>(a_rd + ((b) * 2 + (h)) * (HT * 2) + m * 2048 + k * 1024)
; #define LDB(dst, b, h) for (int n = 0; n < 2; ++n) for (int k = 0; k < 2; ++k) \
;     dst[n][k] = *reinterpret_cast<const bf16x8*>(b_rd + ((b) * 2 + (h)) * (HT * 2) + n * 2048 + k * 1024)
; #define MMA(ai, bj, At_, Bt_) do { __builtin_amdgcn_s_setprio(1); \
;     for (int m = 0; m < 4; ++m) for (int n = 0; n < 2; ++n) for (int k = 0; k < 2; ++k) \
;       acc[ai][bj][m][n] = __builtin_amdgcn_mfma_f32_16x16x32_bf16(Bt_[n][k], At_[m][k], acc[ai][bj][m][n], 0, 0, 0); \
;     __builtin_amdgcn_s_setprio(0); } while (0)
; #define WAIT_V(n) asm volatile("s_waitcnt vmcnt(" #n ")" ::: "memory")
; #define WAIT_L(n) asm volatile("s_waitcnt lgkmcnt(" #n ")" ::: "memory")
; #define BAR __builtin_amdgcn_s_barrier()
;     ...
;   float ssv[2][4] = {};
;   if constexpr (EPI == EPI_GU || EPI == EPI_EVIN || EPI == EPI_ODIN) {
; #pragma unroll
;     for (int ai = 0; ai < 2; ++ai)
; #pragma unroll
;       for (int m = 0; m < 4; ++m) ssv[ai][m] = G.ssr[brow + ai * HALF + wr * 64 + m * 16 + fr];
;   }
;   { LDB(B0, 0, 0); LDA(At, 0, 0); STAGE_A(SA(1, 1), brow + HALF, nt - 1);
;     BAR; WAIT_L(0); MMA(0, 0, At, B0); BAR;
;     LDB(B1, 0, 1); BAR; WAIT_L(0); MMA(0, 1, At, B1); BAR;
;     LDA(At, 0, 1); WAIT_V(4); BAR; WAIT_L(0); MMA(1, 0, At, B0); MMA(1, 1, At, B1); BAR; }
.Lmy_kexit_2:
	s_waitcnt vmcnt(6)
	v_not_b32_e32 v250, 63
	v_mov_b32_e32 v251, 0x41b17218
	v_or_b32_e32 v130, s29, v144
	v_lshl_add_u32 v130, v143, 6, v130
	v_ashrrev_i32_e32 v131, 31, v130
	v_add_u32_e32 v142, 0xa0, v130
	v_lshl_add_u64 v[132:133], v[130:131], 2, s[20:21]
	v_add_u32_e32 v134, 0x80, v130
	v_add_u32_e32 v136, 0x90, v130
	v_ashrrev_i32_e32 v143, 31, v142
	v_add_u32_e32 v130, 0xb0, v130
	s_or_b32 s42, s29, 0x80
	v_ashrrev_i32_e32 v135, 31, v134
	v_ashrrev_i32_e32 v137, 31, v136
	v_lshl_add_u64 v[142:143], v[142:143], 2, s[20:21]
	v_ashrrev_i32_e32 v131, 31, v130
	s_mul_i32 s26, s42, 0x1080
	v_lshl_add_u64 v[134:135], v[134:135], 2, s[20:21]
	v_lshl_add_u64 v[136:137], v[136:137], 2, s[20:21]
	v_lshl_add_u64 v[160:161], v[130:131], 2, s[20:21]
	global_load_dword v130, v[132:133], off
	global_load_dword v152, v[132:133], off offset:64
	global_load_dword v151, v[132:133], off offset:128
	global_load_dword v150, v[132:133], off offset:192
	global_load_dword v145, v[134:135], off
	global_load_dword v144, v[136:137], off
	s_nop 0
	global_load_dword v143, v[142:143], off
	s_nop 0
	global_load_dword v142, v[160:161], off
	s_mul_hi_i32 s27, s42, 0x1080
	s_add_u32 s26, s37, s26
	s_addc_u32 s27, s38, s27
	v_lshl_add_u64 v[136:137], s[26:27], 0, v[180:181]
	s_mov_b64 s[44:45], 0xf80
	v_readfirstlane_b32 s30, v158
	v_lshl_add_u64 v[136:137], v[136:137], 0, s[44:45]
	s_mov_b32 m0, s30
	ds_read_b128 v[132:135], v149
	ds_read_b128 v[160:163], v149 offset:1024
	ds_read_b128 v[164:167], v149 offset:2048
	ds_read_b128 v[168:171], v149 offset:3072
	ds_read_b128 v[172:175], v148
	ds_read_b128 v[176:179], v148 offset:1024
	ds_read_b128 v[182:185], v148 offset:2048
	ds_read_b128 v[186:189], v148 offset:3072
	ds_read_b128 v[190:193], v148 offset:4096
	ds_read_b128 v[194:197], v148 offset:5120
	ds_read_b128 v[198:201], v148 offset:6144
	ds_read_b128 v[202:205], v148 offset:7168
	global_load_lds_dwordx4 v[136:137], off
	v_lshl_add_u64 v[136:137], s[26:27], 0, v[128:129]
	v_readfirstlane_b32 s26, v159
	v_lshl_add_u64 v[136:137], v[136:137], 0, s[44:45]
	s_mov_b32 m0, s26
	s_nop 0
	global_load_lds_dwordx4 v[136:137], off
	s_barrier
	s_waitcnt lgkmcnt(0)
	s_setprio 1
	s_waitcnt lgkmcnt(0)
	v_mfma_f32_16x16x32_bf16 v[124:127], v[132:135], v[172:175], v[124:127]
	v_mfma_f32_16x16x32_bf16 v[120:123], v[164:167], v[172:175], v[120:123]
	v_mfma_f32_16x16x32_bf16 v[116:119], v[132:135], v[182:185], v[116:119]
	v_mfma_f32_16x16x32_bf16 v[112:115], v[164:167], v[182:185], v[112:115]
	v_mfma_f32_16x16x32_bf16 v[108:111], v[132:135], v[190:193], v[108:111]
	v_mfma_f32_16x16x32_bf16 v[104:107], v[164:167], v[190:193], v[104:107]
	v_mfma_f32_16x16x32_bf16 v[100:103], v[132:135], v[198:201], v[100:103]
	v_mfma_f32_16x16x32_bf16 v[96:99], v[164:167], v[198:201], v[96:99]
	v_mfma_f32_16x16x32_bf16 v[124:127], v[160:163], v[176:179], v[124:127]
	v_mfma_f32_16x16x32_bf16 v[120:123], v[168:171], v[176:179], v[120:123]
	v_mfma_f32_16x16x32_bf16 v[116:119], v[160:163], v[186:189], v[116:119]
	v_mfma_f32_16x16x32_bf16 v[112:115], v[168:171], v[186:189], v[112:115]
	v_mfma_f32_16x16x32_bf16 v[108:111], v[160:163], v[194:197], v[108:111]
	v_mfma_f32_16x16x32_bf16 v[104:107], v[168:171], v[194:197], v[104:107]
	s_setprio 2
	s_barrier
	v_mfma_f32_16x16x32_bf16 v[100:103], v[160:163], v[202:205], v[100:103]
	v_mfma_f32_16x16x32_bf16 v[96:99], v[168:171], v[202:205], v[96:99]
	s_setprio 0
	ds_read_b128 v[206:209], v149 offset:16384
	ds_read_b128 v[210:213], v149 offset:17408
	ds_read_b128 v[214:217], v149 offset:18432
	ds_read_b128 v[218:221], v149 offset:19456
	s_barrier
	s_waitcnt lgkmcnt(0)
	s_setprio 1
	s_waitcnt lgkmcnt(0)
	v_mfma_f32_16x16x32_bf16 v[92:95], v[206:209], v[172:175], v[92:95]
	v_mfma_f32_16x16x32_bf16 v[88:91], v[214:217], v[172:175], v[88:91]
	v_mfma_f32_16x16x32_bf16 v[84:87], v[206:209], v[182:185], v[84:87]
	v_mfma_f32_16x16x32_bf16 v[80:83], v[214:217], v[182:185], v[80:83]
	v_mfma_f32_16x16x32_bf16 v[76:79], v[206:209], v[190:193], v[76:79]
	v_mfma_f32_16x16x32_bf16 v[72:75], v[214:217], v[190:193], v[72:75]
	v_mfma_f32_16x16x32_bf16 v[68:71], v[206:209], v[198:201], v[68:71]
	v_mfma_f32_16x16x32_bf16 v[64:67], v[214:217], v[198:201], v[64:67]
	v_mfma_f32_16x16x32_bf16 v[92:95], v[210:213], v[176:179], v[92:95]
	v_mfma_f32_16x16x32_bf16 v[88:91], v[218:221], v[176:179], v[88:91]
	v_mfma_f32_16x16x32_bf16 v[84:87], v[210:213], v[186:189], v[84:87]
	v_mfma_f32_16x16x32_bf16 v[80:83], v[218:221], v[186:189], v[80:83]
	v_mfma_f32_16x16x32_bf16 v[76:79], v[210:213], v[194:197], v[76:79]
	v_mfma_f32_16x16x32_bf16 v[72:75], v[218:221], v[194:197], v[72:75]
	s_setprio 2
	s_barrier
	v_mfma_f32_16x16x32_bf16 v[68:71], v[210:213], v[202:205], v[68:71]
	v_mfma_f32_16x16x32_bf16 v[64:67], v[218:221], v[202:205], v[64:67]
	s_setprio 0
	ds_read_b128 v[172:175], v148 offset:16384
	ds_read_b128 v[176:179], v148 offset:17408
	ds_read_b128 v[182:185], v148 offset:18432
	ds_read_b128 v[186:189], v148 offset:19456
	ds_read_b128 v[190:193], v148 offset:20480
	ds_read_b128 v[194:197], v148 offset:21504
	ds_read_b128 v[198:201], v148 offset:22528
	ds_read_b128 v[202:205], v148 offset:23552
	s_waitcnt vmcnt(4)
	s_barrier
; #define STAGE_A(P, br, kt) do { const char* _base = (const char*)(((kt) < G.ksplit ? G.A1 : A2m) + (long)(br) * G.lda + (long)(kt) * BK); \
;     __builtin_amdgcn_global_load_lds((const unsigned*)(_base + aoff0), (unsigned*)((char*)(P) + sb0), 16, 0, 0); \
;     __builtin_amdgcn_global_load_lds((const unsigned*)(_base + aoff1), (unsigned*)((char*)(P) + sb1), 16, 0, 0); } while (0)
; #define LDA(dst, b, h) for (int m = 0; m < 4; ++m) for (int k = 0; k < 2; ++k) \
;     dst[m][k] = *reinterpret_cast<const bf16x8*>(a_rd + ((b) * 2 + (h)) * (HT * 2) + m * 2048 + k * 1024)
; #define LDB(dst, b, h) for (int n = 0; n < 2; ++n) for (int k = 0; k < 2; ++k) \
;     dst[n][k] = *reinterpret_cast<const bf16x8*>(b_rd + ((b) * 2 + (h)) * (HT * 2) + n * 2048 + k * 1024)
; #define MMA(ai, bj, At_, Bt_) do { __builtin_amdgcn_s_setprio(1); \
;     for (int m = 0; m < 4; ++m) for (int n = 0; n < 2; ++n) for (int k = 0; k < 2; ++k) \
;       acc[ai][bj][m][n] = __builtin_amdgcn_mfma_f32_16x16x32_bf16(Bt_[n][k], At_[m][k], acc[ai][bj][m][n], 0, 0, 0); \
;     __builtin_amdgcn_s_setprio(0); } while (0)
; #define WAIT_V(n) asm volatile("s_waitcnt vmcnt(" #n ")" ::: "memory")
; #define WAIT_L(n) asm volatile("s_waitcnt lgkmcnt(" #n ")" ::: "memory")
; #define BAR __builtin_amdgcn_s_barrier()
;     ...
;   { LDB(B0, 0, 0); LDA(At, 0, 0); STAGE_A(SA(1, 1), brow + HALF, nt - 1);
;     BAR; WAIT_L(0); MMA(0, 0, At, B0); BAR;
;     LDB(B1, 0, 1); BAR; WAIT_L(0); MMA(0, 1, At, B1); BAR;
;     LDA(At, 0, 1); WAIT_V(4); BAR; WAIT_L(0); MMA(1, 0, At, B0); MMA(1, 1, At, B1); BAR; }
;   { LDB(B0, 1, 0); LDA(At, 1, 0); WAIT_V(2); BAR; WAIT_L(0); MMA(0, 0, At, B0); BAR;
;     LDB(B1, 1, 1); WAIT_V(0); BAR; WAIT_L(0); MMA(0, 1, At, B1); BAR;
;     LDA(At, 1, 1); BAR; WAIT_L(0); MMA(1, 0, At, B0); MMA(1, 1, At, B1); BAR; }
	s_waitcnt lgkmcnt(0)
	s_setprio 1
	s_waitcnt lgkmcnt(0)
	v_mfma_f32_16x16x32_bf16 v[60:63], v[132:135], v[172:175], v[60:63]
	v_mfma_f32_16x16x32_bf16 v[56:59], v[164:167], v[172:175], v[56:59]
	v_mfma_f32_16x16x32_bf16 v[52:55], v[132:135], v[182:185], v[52:55]
	v_mfma_f32_16x16x32_bf16 v[48:51], v[164:167], v[182:185], v[48:51]
	v_mfma_f32_16x16x32_bf16 v[44:47], v[132:135], v[190:193], v[44:47]
	v_mfma_f32_16x16x32_bf16 v[40:43], v[164:167], v[190:193], v[40:43]
	v_mfma_f32_16x16x32_bf16 v[36:39], v[132:135], v[198:201], v[36:39]
	v_mfma_f32_16x16x32_bf16 v[32:35], v[164:167], v[198:201], v[32:35]
	v_mfma_f32_16x16x32_bf16 v[60:63], v[160:163], v[176:179], v[60:63]
	v_mfma_f32_16x16x32_bf16 v[56:59], v[168:171], v[176:179], v[56:59]
	v_mfma_f32_16x16x32_bf16 v[52:55], v[160:163], v[186:189], v[52:55]
	v_mfma_f32_16x16x32_bf16 v[48:51], v[168:171], v[186:189], v[48:51]
	v_mfma_f32_16x16x32_bf16 v[44:47], v[160:163], v[194:197], v[44:47]
	v_mfma_f32_16x16x32_bf16 v[40:43], v[168:171], v[194:197], v[40:43]
	v_mfma_f32_16x16x32_bf16 v[36:39], v[160:163], v[202:205], v[36:39]
	v_mfma_f32_16x16x32_bf16 v[32:35], v[168:171], v[202:205], v[32:35]
	s_setprio 0
	s_setprio 1
	v_mfma_f32_16x16x32_bf16 v[28:31], v[206:209], v[172:175], v[28:31]
	v_mfma_f32_16x16x32_bf16 v[24:27], v[214:217], v[172:175], v[24:27]
	v_mfma_f32_16x16x32_bf16 v[20:23], v[206:209], v[182:185], v[20:23]
	v_mfma_f32_16x16x32_bf16 v[16:19], v[214:217], v[182:185], v[16:19]
	v_mfma_f32_16x16x32_bf16 v[12:15], v[206:209], v[190:193], v[12:15]
	v_mfma_f32_16x16x32_bf16 v[8:11], v[214:217], v[190:193], v[8:11]
	v_mfma_f32_16x16x32_bf16 v[4:7], v[206:209], v[198:201], v[4:7]
	v_mfma_f32_16x16x32_bf16 v[0:3], v[214:217], v[198:201], v[0:3]
	v_mfma_f32_16x16x32_bf16 v[28:31], v[210:213], v[176:179], v[28:31]
	v_mfma_f32_16x16x32_bf16 v[24:27], v[218:221], v[176:179], v[24:27]
	v_mfma_f32_16x16x32_bf16 v[20:23], v[210:213], v[186:189], v[20:23]
	v_mfma_f32_16x16x32_bf16 v[16:19], v[218:221], v[186:189], v[16:19]
	v_mfma_f32_16x16x32_bf16 v[12:15], v[210:213], v[194:197], v[12:15]
	v_mfma_f32_16x16x32_bf16 v[8:11], v[218:221], v[194:197], v[8:11]
	s_setprio 2
	s_barrier
	v_mfma_f32_16x16x32_bf16 v[4:7], v[210:213], v[202:205], v[4:7]
	v_mfma_f32_16x16x32_bf16 v[0:3], v[218:221], v[202:205], v[0:3]
	s_setprio 0
	ds_read_b128 v[132:135], v149 offset:32768
	ds_read_b128 v[158:161], v149 offset:33792
	ds_read_b128 v[162:165], v149 offset:34816
	ds_read_b128 v[166:169], v149 offset:35840
	ds_read_b128 v[170:173], v148 offset:32768
	ds_read_b128 v[174:177], v148 offset:33792
	ds_read_b128 v[182:185], v148 offset:34816
	ds_read_b128 v[186:189], v148 offset:35840
	ds_read_b128 v[190:193], v148 offset:36864
	ds_read_b128 v[194:197], v148 offset:37888
	ds_read_b128 v[198:201], v148 offset:38912
	ds_read_b128 v[202:205], v148 offset:39936
	s_waitcnt vmcnt(2)
	s_barrier
	s_waitcnt lgkmcnt(0)
	s_setprio 1
	s_waitcnt lgkmcnt(0)
	v_mfma_f32_16x16x32_bf16 v[124:127], v[132:135], v[170:173], v[124:127]
	v_mfma_f32_16x16x32_bf16 v[120:123], v[162:165], v[170:173], v[120:123]
	v_mfma_f32_16x16x32_bf16 v[116:119], v[132:135], v[182:185], v[116:119]
	v_mfma_f32_16x16x32_bf16 v[112:115], v[162:165], v[182:185], v[112:115]
	v_mfma_f32_16x16x32_bf16 v[108:111], v[132:135], v[190:193], v[108:111]
	v_mfma_f32_16x16x32_bf16 v[104:107], v[162:165], v[190:193], v[104:107]
	v_mfma_f32_16x16x32_bf16 v[100:103], v[132:135], v[198:201], v[100:103]
	v_mfma_f32_16x16x32_bf16 v[96:99], v[162:165], v[198:201], v[96:99]
	v_mfma_f32_16x16x32_bf16 v[124:127], v[158:161], v[174:177], v[124:127]
	v_mfma_f32_16x16x32_bf16 v[120:123], v[166:169], v[174:177], v[120:123]
	v_mfma_f32_16x16x32_bf16 v[116:119], v[158:161], v[186:189], v[116:119]
	v_mfma_f32_16x16x32_bf16 v[112:115], v[166:169], v[186:189], v[112:115]
	v_mfma_f32_16x16x32_bf16 v[108:111], v[158:161], v[194:197], v[108:111]
	v_mfma_f32_16x16x32_bf16 v[104:107], v[166:169], v[194:197], v[104:107]
	s_setprio 2
	s_barrier
	v_mfma_f32_16x16x32_bf16 v[100:103], v[158:161], v[202:205], v[100:103]
	v_mfma_f32_16x16x32_bf16 v[96:99], v[166:169], v[202:205], v[96:99]
	s_setprio 0
	ds_read_b128 v[206:209], v149 offset:49152
	ds_read_b128 v[210:213], v149 offset:50176
	ds_read_b128 v[214:217], v149 offset:51200
	ds_read_b128 v[218:221], v149 offset:52224
	s_waitcnt vmcnt(0)
	s_barrier
	s_waitcnt lgkmcnt(0)
	s_setprio 1
	s_waitcnt lgkmcnt(0)
	v_mfma_f32_16x16x32_bf16 v[92:95], v[206:209], v[170:173], v[92:95]
	v_mfma_f32_16x16x32_bf16 v[88:91], v[214:217], v[170:173], v[88:91]
	v_mfma_f32_16x16x32_bf16 v[84:87], v[206:209], v[182:185], v[84:87]
	v_mfma_f32_16x16x32_bf16 v[80:83], v[214:217], v[182:185], v[80:83]
	v_mfma_f32_16x16x32_bf16 v[76:79], v[206:209], v[190:193], v[76:79]
	v_mfma_f32_16x16x32_bf16 v[72:75], v[214:217], v[190:193], v[72:75]
	v_mfma_f32_16x16x32_bf16 v[68:71], v[206:209], v[198:201], v[68:71]
	v_mfma_f32_16x16x32_bf16 v[64:67], v[214:217], v[198:201], v[64:67]
	v_mfma_f32_16x16x32_bf16 v[92:95], v[210:213], v[174:177], v[92:95]
	v_mfma_f32_16x16x32_bf16 v[88:91], v[218:221], v[174:177], v[88:91]
	v_mfma_f32_16x16x32_bf16 v[84:87], v[210:213], v[186:189], v[84:87]
	v_mfma_f32_16x16x32_bf16 v[80:83], v[218:221], v[186:189], v[80:83]
	v_mfma_f32_16x16x32_bf16 v[76:79], v[210:213], v[194:197], v[76:79]
	v_mfma_f32_16x16x32_bf16 v[72:75], v[218:221], v[194:197], v[72:75]
	s_setprio 2
	s_barrier
; #define STAGE_A(P, br, kt) do { const char* _base = (const char*)(((kt) < G.ksplit ? G.A1 : A2m) + (long)(br) * G.lda + (long)(kt) * BK); \
;     __builtin_amdgcn_global_load_lds((const unsigned*)(_base + aoff0), (unsigned*)((char*)(P) + sb0), 16, 0, 0); \
;     __builtin_amdgcn_global_load_lds((const unsigned*)(_base + aoff1), (unsigned*)((char*)(P) + sb1), 16, 0, 0); } while (0)
; #define STAGE_B(P, br, kt) do { const char* _base = (const char*)(G.Bt + (long)(br) * G.ldb + (long)(kt) * BK); \
;     __builtin_amdgcn_global_load_lds((const unsigned*)(_base + boff0), (unsigned*)((char*)(P) + sb0), 16, 0, 0); \
;     __builtin_amdgcn_global_load_lds((const unsigned*)(_base + boff1), (unsigned*)((char*)(P) + sb1), 16, 0, 0); } while (0)
; #define LDA(dst, b, h) for (int m = 0; m < 4; ++m) for (int k = 0; k < 2; ++k) \
;     dst[m][k] = *reinterpret_cast<const bf16x8*>(a_rd + ((b) * 2 + (h)) * (HT * 2) + m * 2048 + k * 1024)
; #define LDB(dst, b, h) for (int n = 0; n < 2; ++n) for (int k = 0; k < 2; ++k) \
;     dst[n][k] = *reinterpret_cast<const bf16x8*>(b_rd + ((b) * 2 + (h)) * (HT * 2) + n * 2048 + k * 1024)
; #define MMA(ai, bj, At_, Bt_) do { __builtin_amdgcn_s_setprio(1); \
;     for (int m = 0; m < 4; ++m) for (int n = 0; n < 2; ++n) for (int k = 0; k < 2; ++k) \
;       acc[ai][bj][m][n] = __builtin_amdgcn_mfma_f32_16x16x32_bf16(Bt_[n][k], At_[m][k], acc[ai][bj][m][n], 0, 0, 0); \
;     __builtin_amdgcn_s_setprio(0); } while (0)
; #define WAIT_V(n) asm volatile("s_waitcnt vmcnt(" #n ")" ::: "memory")
; #define WAIT_L(n) asm volatile("s_waitcnt lgkmcnt(" #n ")" ::: "memory")
; #define BAR __builtin_amdgcn_s_barrier()
;     ...
;   { LDB(B0, 1, 0); LDA(At, 1, 0); WAIT_V(2); BAR; WAIT_L(0); MMA(0, 0, At, B0); BAR;
;     LDB(B1, 1, 1); WAIT_V(0); BAR; WAIT_L(0); MMA(0, 1, At, B1); BAR;
;     LDA(At, 1, 1); BAR; WAIT_L(0); MMA(1, 0, At, B0); MMA(1, 1, At, B1); BAR; }
;   if (wr == 0) BAR;
;   if (EPI != EPI_RESID && has_next) {
;     STAGE_B(SB(0, 0), nbcol, 0); STAGE_A(SA(0, 0), nbrow, 0);
;     STAGE_B(SB(0, 1), nbcol + HALF, 0); STAGE_A(SA(0, 1), nbrow + HALF, 0);
;   }
	v_mfma_f32_16x16x32_bf16 v[68:71], v[210:213], v[202:205], v[68:71]
	v_mfma_f32_16x16x32_bf16 v[64:67], v[218:221], v[202:205], v[64:67]
	s_setprio 0
	ds_read_b128 v[170:173], v148 offset:49152
	ds_read_b128 v[174:177], v148 offset:50176
	ds_read_b128 v[182:185], v148 offset:51200
	ds_read_b128 v[186:189], v148 offset:52224
	ds_read_b128 v[190:193], v148 offset:53248
	ds_read_b128 v[194:197], v148 offset:54272
	ds_read_b128 v[198:201], v148 offset:55296
	ds_read_b128 v[202:205], v148 offset:56320
	s_barrier
	s_waitcnt lgkmcnt(0)
	s_setprio 1
	s_waitcnt lgkmcnt(0)
	v_mfma_f32_16x16x32_bf16 v[60:63], v[132:135], v[170:173], v[60:63]
	v_mfma_f32_16x16x32_bf16 v[56:59], v[162:165], v[170:173], v[56:59]
	v_mfma_f32_16x16x32_bf16 v[52:55], v[132:135], v[182:185], v[52:55]
	v_mfma_f32_16x16x32_bf16 v[48:51], v[162:165], v[182:185], v[48:51]
	v_mfma_f32_16x16x32_bf16 v[44:47], v[132:135], v[190:193], v[44:47]
	v_mfma_f32_16x16x32_bf16 v[40:43], v[162:165], v[190:193], v[40:43]
	v_mfma_f32_16x16x32_bf16 v[36:39], v[132:135], v[198:201], v[36:39]
	v_mfma_f32_16x16x32_bf16 v[32:35], v[162:165], v[198:201], v[32:35]
	v_mfma_f32_16x16x32_bf16 v[60:63], v[158:161], v[174:177], v[60:63]
	v_mfma_f32_16x16x32_bf16 v[56:59], v[166:169], v[174:177], v[56:59]
	v_mfma_f32_16x16x32_bf16 v[52:55], v[158:161], v[186:189], v[52:55]
	v_mfma_f32_16x16x32_bf16 v[48:51], v[166:169], v[186:189], v[48:51]
	v_mfma_f32_16x16x32_bf16 v[44:47], v[158:161], v[194:197], v[44:47]
	v_mfma_f32_16x16x32_bf16 v[40:43], v[166:169], v[194:197], v[40:43]
	v_mfma_f32_16x16x32_bf16 v[36:39], v[158:161], v[202:205], v[36:39]
	v_mfma_f32_16x16x32_bf16 v[32:35], v[166:169], v[202:205], v[32:35]
	s_setprio 0
	s_setprio 1
	v_mfma_f32_16x16x32_bf16 v[28:31], v[206:209], v[170:173], v[28:31]
	v_mfma_f32_16x16x32_bf16 v[24:27], v[214:217], v[170:173], v[24:27]
	v_mfma_f32_16x16x32_bf16 v[20:23], v[206:209], v[182:185], v[20:23]
	v_mfma_f32_16x16x32_bf16 v[16:19], v[214:217], v[182:185], v[16:19]
	v_mfma_f32_16x16x32_bf16 v[12:15], v[206:209], v[190:193], v[12:15]
	v_mfma_f32_16x16x32_bf16 v[8:11], v[214:217], v[190:193], v[8:11]
	v_mfma_f32_16x16x32_bf16 v[4:7], v[206:209], v[198:201], v[4:7]
	v_mfma_f32_16x16x32_bf16 v[0:3], v[214:217], v[198:201], v[0:3]
	v_mfma_f32_16x16x32_bf16 v[28:31], v[210:213], v[174:177], v[28:31]
	v_mfma_f32_16x16x32_bf16 v[24:27], v[218:221], v[174:177], v[24:27]
	v_mfma_f32_16x16x32_bf16 v[20:23], v[210:213], v[186:189], v[20:23]
	v_mfma_f32_16x16x32_bf16 v[16:19], v[218:221], v[186:189], v[16:19]
	v_mfma_f32_16x16x32_bf16 v[12:15], v[210:213], v[194:197], v[12:15]
	v_mfma_f32_16x16x32_bf16 v[8:11], v[218:221], v[194:197], v[8:11]
	s_setprio 2
	s_barrier
	v_mfma_f32_16x16x32_bf16 v[4:7], v[210:213], v[202:205], v[4:7]
	v_mfma_f32_16x16x32_bf16 v[0:3], v[218:221], v[202:205], v[0:3]
	s_setprio 0
	s_andn2_b64 vcc, exec, s[6:7]
	s_cbranch_vccnz .LBB0_1870
	s_lshl_b64 s[6:7], s[8:9], 1
	s_add_u32 s6, s39, s6
	s_addc_u32 s7, s40, s7
	v_readfirstlane_b32 s8, v155
	v_lshl_add_u64 v[132:133], s[6:7], 0, v[180:181]
	s_mov_b32 m0, s8
	v_readfirstlane_b32 s8, v156
	s_mul_i32 s26, s28, 0x1080
	global_load_lds_dwordx4 v[132:133], off
	s_mov_b32 m0, s8
	s_mul_hi_i32 s9, s28, 0x1080
	s_add_u32 s8, s37, s26
	v_lshl_add_u64 v[132:133], s[6:7], 0, v[128:129]
	s_addc_u32 s9, s38, s9
	v_readfirstlane_b32 s27, v147
	global_load_lds_dwordx4 v[132:133], off
	v_lshl_add_u64 v[132:133], s[8:9], 0, v[180:181]
	s_mov_b32 m0, s27
	s_add_u32 s6, s6, 0x84000
	global_load_lds_dwordx4 v[132:133], off
	v_lshl_add_u64 v[132:133], s[8:9], 0, v[128:129]
	v_readfirstlane_b32 s8, v146
	s_mov_b32 m0, s8
	s_addc_u32 s7, s7, 0
	v_readfirstlane_b32 s8, v141
	global_load_lds_dwordx4 v[132:133], off
	v_lshl_add_u64 v[132:133], s[6:7], 0, v[180:181]
	s_mov_b32 m0, s8
	s_add_i32 s26, s26, 0x84000
	global_load_lds_dwordx4 v[132:133], off
	v_lshl_add_u64 v[132:133], s[6:7], 0, v[128:129]
	v_readfirstlane_b32 s6, v157
	s_mov_b32 m0, s6
	s_add_i32 s6, s28, 0x80
	s_mul_hi_i32 s7, s6, 0x1080
	s_add_u32 s6, s37, s26
	s_addc_u32 s7, s38, s7
	v_readfirstlane_b32 s8, v140
	global_load_lds_dwordx4 v[132:133], off
	v_lshl_add_u64 v[132:133], s[6:7], 0, v[180:181]
	s_mov_b32 m0, s8
	v_lshl_add_u64 v[128:129], s[6:7], 0, v[128:129]
	v_readfirstlane_b32 s6, v138
	global_load_lds_dwordx4 v[132:133], off
	s_mov_b32 m0, s6
	s_nop 0
	global_load_lds_dwordx4 v[128:129], off
